# asm guide 7.12 rule (delete what recomputes known values): v47 + FOX/DIFF row-sum chains start with a+b instead of (0+a)+b (4 sites, bit-identical)
# speedup vs baseline: 1.0006x; 1.0006x over previous
.LBB0_318:
	v_exp_f32_e32 v84, v68
	v_exp_f32_e32 v85, v69
	v_exp_f32_e32 v86, v70
	v_exp_f32_e32 v71, v71
	v_exp_f32_e32 v72, v72
	v_add_f32_e32 v68, v85, v84
	v_exp_f32_e32 v73, v73
	v_add_f32_e32 v68, v86, v68
	v_exp_f32_e32 v74, v74
	v_add_f32_e32 v68, v71, v68
	v_exp_f32_e32 v75, v75
	v_add_f32_e32 v68, v72, v68
	v_exp_f32_e32 v76, v76
	v_add_f32_e32 v68, v73, v68
	v_exp_f32_e32 v77, v77
	v_add_f32_e32 v68, v74, v68
	v_exp_f32_e32 v78, v78
	v_add_f32_e32 v68, v75, v68
	v_exp_f32_e32 v79, v79
	v_add_f32_e32 v68, v76, v68
	v_exp_f32_e32 v80, v80
	v_add_f32_e32 v68, v77, v68
	v_exp_f32_e32 v81, v81
	v_add_f32_e32 v68, v78, v68
	v_exp_f32_e32 v82, v82
	v_add_f32_e32 v68, v79, v68
	v_exp_f32_e32 v83, v83
	v_add_f32_e32 v68, v80, v68
	v_exp_f32_e32 v52, v52
	v_add_f32_e32 v68, v81, v68
	v_exp_f32_e32 v53, v53
	v_add_f32_e32 v68, v82, v68
	v_exp_f32_e32 v54, v54
	v_add_f32_e32 v68, v83, v68
	v_exp_f32_e32 v55, v55
	v_add_f32_e32 v68, v52, v68
	v_exp_f32_e32 v56, v56
	v_add_f32_e32 v68, v53, v68
	v_exp_f32_e32 v57, v57
	v_add_f32_e32 v68, v54, v68
	v_exp_f32_e32 v58, v58
	v_add_f32_e32 v68, v55, v68
	v_exp_f32_e32 v59, v59
	v_add_f32_e32 v68, v56, v68
	v_exp_f32_e32 v60, v60
	v_add_f32_e32 v68, v57, v68
	v_exp_f32_e32 v61, v61
	v_add_f32_e32 v68, v58, v68
	v_exp_f32_e32 v62, v62
	v_add_f32_e32 v68, v59, v68
	v_exp_f32_e32 v63, v63
	v_exp_f32_e32 v64, v64
	v_exp_f32_e32 v65, v65
	v_exp_f32_e32 v66, v66
	v_exp_f32_e32 v67, v67
	v_cvt_pk_bf16_f32 v70, v84, v85
	v_cvt_pk_bf16_f32 v71, v86, v71
	v_cvt_pk_bf16_f32 v72, v72, v73
	v_cvt_pk_bf16_f32 v73, v74, v75
	v_cvt_pk_bf16_f32 v74, v76, v77
	v_cvt_pk_bf16_f32 v75, v78, v79
	v_cvt_pk_bf16_f32 v76, v80, v81
	v_cvt_pk_bf16_f32 v77, v82, v83
	v_cvt_pk_bf16_f32 v78, v52, v53
	v_cvt_pk_bf16_f32 v79, v54, v55
	v_cvt_pk_bf16_f32 v80, v56, v57
	v_cvt_pk_bf16_f32 v81, v58, v59
	v_cvt_pk_bf16_f32 v118, v60, v61
	v_cvt_pk_bf16_f32 v119, v62, v63
	v_cvt_pk_bf16_f32 v120, v64, v65
	v_cvt_pk_bf16_f32 v121, v66, v67
	ds_read_b64_tr_b16 v[82:83], v236 offset:0
	v_add_f32_e32 v68, v60, v68
	ds_read_b64_tr_b16 v[84:85], v236 offset:0x800
	v_add_f32_e32 v68, v61, v68
	ds_read_b64_tr_b16 v[86:87], v236 offset:0x1000
	v_add_f32_e32 v68, v62, v68
	ds_read_b64_tr_b16 v[88:89], v236 offset:0x1800
	v_add_f32_e32 v68, v63, v68
	ds_read_b64_tr_b16 v[90:91], v236 offset:0x2000
	v_add_f32_e32 v68, v64, v68
	ds_read_b64_tr_b16 v[92:93], v236 offset:0x2800
	v_add_f32_e32 v68, v65, v68
	ds_read_b64_tr_b16 v[94:95], v236 offset:0x3000
	v_add_f32_e32 v68, v66, v68
	ds_read_b64_tr_b16 v[96:97], v236 offset:0x3800
	v_add_f32_e32 v68, v67, v68
	s_waitcnt lgkmcnt(0)
	v_mov_b32_e32 v69, v68
	s_nop 1
	v_permlane32_swap_b32_e32 v68, v69
	v_permlane32_swap_b32_e32 v70, v72
	v_permlane32_swap_b32_e32 v71, v73
	v_permlane32_swap_b32_e32 v74, v76
	v_permlane32_swap_b32_e32 v75, v77
	v_permlane32_swap_b32_e32 v78, v80
	v_permlane32_swap_b32_e32 v79, v81
	v_permlane32_swap_b32_e32 v118, v120
	v_permlane32_swap_b32_e32 v119, v121
	v_mfma_f32_32x32x16_bf16 v[52:67], v[70:73], v[82:85], v[36:51]
	ds_read_b64_tr_b16 v[100:101], v236 offset:0x200
	ds_read_b64_tr_b16 v[102:103], v236 offset:0xa00
	ds_read_b64_tr_b16 v[104:105], v236 offset:0x1200
	ds_read_b64_tr_b16 v[106:107], v236 offset:0x1a00
	ds_read_b64_tr_b16 v[108:109], v236 offset:0x2200
	ds_read_b64_tr_b16 v[110:111], v236 offset:0x2a00
	ds_read_b64_tr_b16 v[112:113], v236 offset:0x3200
	v_mfma_f32_32x32x16_bf16 v[52:67], v[74:77], v[86:89], v[52:67]
	ds_read_b64_tr_b16 v[114:115], v236 offset:0x3a00
	s_waitcnt lgkmcnt(0)
	v_mfma_f32_32x32x16_bf16 v[52:67], v[78:81], v[90:93], v[52:67]
	v_mfma_f32_32x32x16_bf16 v[52:67], v[118:121], v[94:97], v[52:67]
	v_mfma_f32_32x32x16_bf16 v[84:99], v[70:73], v[100:103], v[36:51]
	ds_read_b64_tr_b16 v[122:123], v236 offset:0x400
	ds_read_b64_tr_b16 v[124:125], v236 offset:0xc00
	ds_read_b64_tr_b16 v[126:127], v236 offset:0x1400
	ds_read_b64_tr_b16 v[128:129], v236 offset:0x1c00
	ds_read_b64_tr_b16 v[148:149], v236 offset:0x2400
	ds_read_b64_tr_b16 v[150:151], v236 offset:0x2c00
	ds_read_b64_tr_b16 v[158:159], v236 offset:0x3400
	v_mfma_f32_32x32x16_bf16 v[84:99], v[74:77], v[104:107], v[84:99]
	ds_read_b64_tr_b16 v[160:161], v236 offset:0x3c00
	s_waitcnt lgkmcnt(0)
	v_mfma_f32_32x32x16_bf16 v[84:99], v[78:81], v[108:111], v[84:99]
	v_mfma_f32_32x32x16_bf16 v[84:99], v[118:121], v[112:115], v[84:99]
	v_mfma_f32_32x32x16_bf16 v[100:115], v[70:73], v[122:125], v[36:51]
	ds_read_b64_tr_b16 v[122:123], v236 offset:0x600
	ds_read_b64_tr_b16 v[124:125], v236 offset:0xe00
	v_mfma_f32_32x32x16_bf16 v[100:115], v[74:77], v[126:129], v[100:115]
	ds_read_b64_tr_b16 v[126:127], v236 offset:0x1600
	ds_read_b64_tr_b16 v[128:129], v236 offset:0x1e00
	v_mfma_f32_32x32x16_bf16 v[100:115], v[78:81], v[148:151], v[100:115]
	ds_read_b64_tr_b16 v[148:149], v236 offset:0x2600
	ds_read_b64_tr_b16 v[150:151], v236 offset:0x2e00
	v_mfma_f32_32x32x16_bf16 v[100:115], v[118:121], v[158:161], v[100:115]
	ds_read_b64_tr_b16 v[158:159], v236 offset:0x3600
	ds_read_b64_tr_b16 v[160:161], v236 offset:0x3e00
	s_waitcnt lgkmcnt(0)
	v_mfma_f32_32x32x16_bf16 v[36:51], v[70:73], v[122:125], v[36:51]
	s_andn2_b64 s[42:43], exec, s[8:9]
	s_andn2_b64 vcc, exec, s[8:9]
	v_mfma_f32_32x32x16_bf16 v[36:51], v[74:77], v[126:129], v[36:51]
	v_mfma_f32_32x32x16_bf16 v[36:51], v[78:81], v[148:151], v[36:51]
	v_mfma_f32_32x32x16_bf16 v[36:51], v[118:121], v[158:161], v[36:51]
	s_cbranch_vccnz .LBB0_320
	v_add_u32_e32 v70, s88, v153
	s_waitcnt vmcnt(2)
	ds_write_b128 v70, v[132:135] offset:32768
	v_add_u32_e32 v70, s89, v224
	s_waitcnt vmcnt(1)
	ds_write_b128 v70, v[136:139]
	v_add_u32_e32 v70, s89, v225
	s_waitcnt vmcnt(0)
	ds_write_b128 v70, v[140:143]

.LBB0_328:
	v_exp_f32_e32 v151, v68
	v_exp_f32_e32 v160, v69
	v_exp_f32_e32 v161, v70
	v_exp_f32_e32 v71, v71
	v_exp_f32_e32 v72, v72
	v_add_f32_e32 v68, v160, v151
	v_exp_f32_e32 v73, v73
	v_add_f32_e32 v68, v161, v68
	v_exp_f32_e32 v74, v74
	v_add_f32_e32 v68, v71, v68
	v_exp_f32_e32 v75, v75
	v_add_f32_e32 v68, v72, v68
	v_exp_f32_e32 v76, v76
	v_add_f32_e32 v68, v73, v68
	v_exp_f32_e32 v77, v77
	v_add_f32_e32 v68, v74, v68
	v_exp_f32_e32 v78, v78
	v_add_f32_e32 v68, v75, v68
	v_exp_f32_e32 v79, v79
	v_add_f32_e32 v68, v76, v68
	v_exp_f32_e32 v80, v80
	v_add_f32_e32 v68, v77, v68
	v_exp_f32_e32 v81, v81
	v_add_f32_e32 v68, v78, v68
	v_exp_f32_e32 v82, v82
	v_add_f32_e32 v68, v79, v68
	v_exp_f32_e32 v83, v83
	v_add_f32_e32 v68, v80, v68
	v_exp_f32_e32 v116, v116
	v_add_f32_e32 v68, v81, v68
	v_exp_f32_e32 v117, v117
	v_add_f32_e32 v68, v82, v68
	v_exp_f32_e32 v118, v118
	v_add_f32_e32 v68, v83, v68
	v_exp_f32_e32 v119, v119
	v_add_f32_e32 v68, v116, v68
	v_exp_f32_e32 v120, v120
	v_add_f32_e32 v68, v117, v68
	v_exp_f32_e32 v121, v121
	v_add_f32_e32 v68, v118, v68
	v_exp_f32_e32 v122, v122
	v_add_f32_e32 v68, v119, v68
	v_exp_f32_e32 v123, v123
	v_add_f32_e32 v68, v120, v68
	v_exp_f32_e32 v124, v124
	v_add_f32_e32 v68, v121, v68
	v_exp_f32_e32 v125, v125
	v_add_f32_e32 v68, v122, v68
	v_exp_f32_e32 v126, v126
	v_add_f32_e32 v68, v123, v68
	v_exp_f32_e32 v127, v127
	v_add_f32_e32 v68, v124, v68
	v_exp_f32_e32 v128, v128
	v_add_f32_e32 v68, v125, v68
	v_exp_f32_e32 v129, v129
	v_add_f32_e32 v68, v126, v68
	v_exp_f32_e32 v130, v130
	v_exp_f32_e32 v131, v131
	v_cvt_pk_bf16_f32 v70, v151, v160
	v_cvt_pk_bf16_f32 v71, v161, v71
	v_cvt_pk_bf16_f32 v72, v72, v73
	v_cvt_pk_bf16_f32 v73, v74, v75
	v_cvt_pk_bf16_f32 v74, v76, v77
	v_cvt_pk_bf16_f32 v75, v78, v79
	v_cvt_pk_bf16_f32 v76, v80, v81
	v_cvt_pk_bf16_f32 v77, v82, v83
	v_cvt_pk_bf16_f32 v78, v116, v117
	v_cvt_pk_bf16_f32 v79, v118, v119
	v_cvt_pk_bf16_f32 v80, v120, v121
	v_cvt_pk_bf16_f32 v81, v122, v123
	v_cvt_pk_bf16_f32 v116, v124, v125
	v_cvt_pk_bf16_f32 v117, v126, v127
	v_cvt_pk_bf16_f32 v118, v128, v129
	v_cvt_pk_bf16_f32 v119, v130, v131
	v_add_u32_e32 v82, s21, v233
	ds_read_b64_tr_b16 v[120:121], v82 offset:0
	v_add_f32_e32 v68, v127, v68
	ds_read_b64_tr_b16 v[122:123], v82 offset:0x800
	v_add_f32_e32 v68, v128, v68
	ds_read_b64_tr_b16 v[124:125], v82 offset:0x1000
	v_add_f32_e32 v68, v129, v68
	ds_read_b64_tr_b16 v[126:127], v82 offset:0x1800
	v_add_f32_e32 v68, v130, v68
	ds_read_b64_tr_b16 v[128:129], v82 offset:0x2000
	v_add_f32_e32 v68, v131, v68
	ds_read_b64_tr_b16 v[130:131], v82 offset:0x2800
	ds_read_b64_tr_b16 v[160:161], v82 offset:0x3000
	ds_read_b64_tr_b16 v[162:163], v82 offset:0x3800
	s_waitcnt lgkmcnt(0)
	v_mov_b32_e32 v69, v68
	s_nop 1
	v_permlane32_swap_b32_e32 v68, v69
	v_permlane32_swap_b32_e32 v70, v72
	v_permlane32_swap_b32_e32 v71, v73
	v_permlane32_swap_b32_e32 v74, v76
	v_permlane32_swap_b32_e32 v75, v77
	v_permlane32_swap_b32_e32 v78, v80
	v_permlane32_swap_b32_e32 v79, v81
	v_permlane32_swap_b32_e32 v116, v118
	v_permlane32_swap_b32_e32 v117, v119
	v_mfma_f32_32x32x16_bf16 v[52:67], v[70:73], v[120:123], v[52:67]
	ds_read_b64_tr_b16 v[120:121], v82 offset:0x200
	ds_read_b64_tr_b16 v[122:123], v82 offset:0xa00
	v_mfma_f32_32x32x16_bf16 v[52:67], v[74:77], v[124:127], v[52:67]
	ds_read_b64_tr_b16 v[124:125], v82 offset:0x1200
	ds_read_b64_tr_b16 v[126:127], v82 offset:0x1a00
	v_mfma_f32_32x32x16_bf16 v[52:67], v[78:81], v[128:131], v[52:67]
	ds_read_b64_tr_b16 v[128:129], v82 offset:0x2200
	ds_read_b64_tr_b16 v[130:131], v82 offset:0x2a00
	v_mfma_f32_32x32x16_bf16 v[52:67], v[116:119], v[160:163], v[52:67]
	ds_read_b64_tr_b16 v[160:161], v82 offset:0x3200
	ds_read_b64_tr_b16 v[162:163], v82 offset:0x3a00
	s_waitcnt lgkmcnt(0)
	v_mfma_f32_32x32x16_bf16 v[84:99], v[70:73], v[120:123], v[84:99]
	ds_read_b64_tr_b16 v[120:121], v82 offset:0x400
	ds_read_b64_tr_b16 v[122:123], v82 offset:0xc00
	v_mfma_f32_32x32x16_bf16 v[84:99], v[74:77], v[124:127], v[84:99]
	ds_read_b64_tr_b16 v[124:125], v82 offset:0x1400
	ds_read_b64_tr_b16 v[126:127], v82 offset:0x1c00
	v_mfma_f32_32x32x16_bf16 v[84:99], v[78:81], v[128:131], v[84:99]
	ds_read_b64_tr_b16 v[128:129], v82 offset:0x2400
	ds_read_b64_tr_b16 v[130:131], v82 offset:0x2c00
	v_mfma_f32_32x32x16_bf16 v[84:99], v[116:119], v[160:163], v[84:99]
	ds_read_b64_tr_b16 v[160:161], v82 offset:0x3400
	ds_read_b64_tr_b16 v[162:163], v82 offset:0x3c00
	s_waitcnt lgkmcnt(0)
	v_mfma_f32_32x32x16_bf16 v[100:115], v[70:73], v[120:123], v[100:115]
	ds_read_b64_tr_b16 v[120:121], v82 offset:0x600
	ds_read_b64_tr_b16 v[122:123], v82 offset:0xe00
	v_mfma_f32_32x32x16_bf16 v[100:115], v[74:77], v[124:127], v[100:115]
	ds_read_b64_tr_b16 v[124:125], v82 offset:0x1600
	ds_read_b64_tr_b16 v[126:127], v82 offset:0x1e00
	v_mfma_f32_32x32x16_bf16 v[100:115], v[78:81], v[128:131], v[100:115]
	ds_read_b64_tr_b16 v[128:129], v82 offset:0x2600
	ds_read_b64_tr_b16 v[130:131], v82 offset:0x2e00
	v_mfma_f32_32x32x16_bf16 v[100:115], v[116:119], v[160:163], v[100:115]
	ds_read_b64_tr_b16 v[160:161], v82 offset:0x3600
	ds_read_b64_tr_b16 v[162:163], v82 offset:0x3e00
	s_waitcnt lgkmcnt(0)
	v_mfma_f32_32x32x16_bf16 v[36:51], v[70:73], v[120:123], v[36:51]
	s_andn2_b64 vcc, exec, s[18:19]
	v_mfma_f32_32x32x16_bf16 v[36:51], v[74:77], v[124:127], v[36:51]
	v_mfma_f32_32x32x16_bf16 v[36:51], v[78:81], v[128:131], v[36:51]
	v_mfma_f32_32x32x16_bf16 v[36:51], v[116:119], v[160:163], v[36:51]
	s_cbranch_vccnz .LBB0_330
	s_xor_b32 s18, s21, 0x4000
	s_add_i32 s19, s18, 0
	v_add_u32_e32 v72, s18, v153
	v_add_u32_e32 v70, s19, v225
	v_add_u32_e32 v71, s19, v224
	s_waitcnt vmcnt(2)
	ds_write_b128 v72, v[132:135] offset:32768
	s_waitcnt vmcnt(1)
	ds_write_b128 v71, v[136:139]
	s_waitcnt vmcnt(0)
	ds_write_b128 v70, v[140:143]

.LBB0_496:
	v_exp_f32_e32 v84, v84
	v_exp_f32_e32 v85, v85
	v_exp_f32_e32 v86, v86
	v_exp_f32_e32 v87, v87
	v_add_f32_e32 v194, v194, v164
	v_exp_f32_e32 v88, v88
	v_add_f32_e32 v164, v85, v84
	v_exp_f32_e32 v89, v89
	v_add_f32_e32 v164, v86, v164
	v_exp_f32_e32 v90, v90
	v_add_f32_e32 v164, v87, v164
	v_exp_f32_e32 v91, v91
	v_add_f32_e32 v164, v88, v164
	v_exp_f32_e32 v92, v92
	v_add_f32_e32 v164, v89, v164
	v_exp_f32_e32 v93, v93
	v_add_f32_e32 v164, v90, v164
	v_exp_f32_e32 v94, v94
	v_add_f32_e32 v164, v91, v164
	v_exp_f32_e32 v95, v95
	v_add_f32_e32 v164, v92, v164
	v_exp_f32_e32 v96, v96
	v_add_f32_e32 v164, v93, v164
	v_exp_f32_e32 v97, v97
	v_add_f32_e32 v164, v94, v164
	v_exp_f32_e32 v98, v98
	v_add_f32_e32 v164, v95, v164
	v_exp_f32_e32 v99, v99
	v_add_f32_e32 v164, v96, v164
	v_exp_f32_e32 v180, v68
	v_add_f32_e32 v164, v97, v164
	v_exp_f32_e32 v181, v69
	v_add_f32_e32 v164, v98, v164
	v_exp_f32_e32 v182, v70
	v_add_f32_e32 v164, v99, v164
	v_exp_f32_e32 v183, v71
	v_add_f32_e32 v68, v180, v164
	v_exp_f32_e32 v164, v72
	v_add_f32_e32 v68, v181, v68
	v_exp_f32_e32 v198, v73
	v_add_f32_e32 v68, v182, v68
	v_exp_f32_e32 v199, v74
	v_add_f32_e32 v68, v183, v68
	v_exp_f32_e32 v200, v75
	v_add_f32_e32 v68, v164, v68
	v_exp_f32_e32 v201, v76
	v_add_f32_e32 v68, v198, v68
	v_exp_f32_e32 v202, v77
	v_add_f32_e32 v68, v199, v68
	v_exp_f32_e32 v203, v78
	v_add_f32_e32 v68, v200, v68
	v_exp_f32_e32 v204, v79
	v_add_f32_e32 v68, v201, v68
	v_exp_f32_e32 v205, v80
	v_add_f32_e32 v68, v202, v68
	v_exp_f32_e32 v206, v81
	v_add_f32_e32 v68, v203, v68
	v_exp_f32_e32 v207, v82
	v_add_f32_e32 v68, v204, v68
	v_exp_f32_e32 v83, v83
	v_add_f32_e32 v68, v205, v68
	v_add_f32_e32 v68, v206, v68
	v_add_f32_e32 v68, v207, v68
	v_add_f32_e32 v68, v83, v68
	v_mov_b32_e32 v69, v68
	s_nop 1
	v_permlane32_swap_b32_e32 v68, v69
	v_add_f32_e32 v208, v68, v69
	v_cvt_pk_bf16_f32 v68, v84, v85
	v_cvt_pk_bf16_f32 v69, v86, v87
	v_cvt_pk_bf16_f32 v70, v88, v89
	v_cvt_pk_bf16_f32 v71, v90, v91
	v_cvt_pk_bf16_f32 v72, v92, v93
	v_cvt_pk_bf16_f32 v73, v94, v95
	v_cvt_pk_bf16_f32 v74, v96, v97
	v_cvt_pk_bf16_f32 v75, v98, v99
	v_cvt_pk_bf16_f32 v76, v180, v181
	v_cvt_pk_bf16_f32 v77, v182, v183
	v_cvt_pk_bf16_f32 v78, v164, v198
	v_cvt_pk_bf16_f32 v79, v199, v200
	v_cvt_pk_bf16_f32 v80, v201, v202
	v_cvt_pk_bf16_f32 v81, v203, v204
	v_cvt_pk_bf16_f32 v82, v205, v206
	v_cvt_pk_bf16_f32 v83, v207, v83
	ds_read_b64_tr_b16 v[84:85], v173 offset:0
	ds_read_b64_tr_b16 v[86:87], v173 offset:0x800
	ds_read_b64_tr_b16 v[88:89], v173 offset:0x1000
	ds_read_b64_tr_b16 v[90:91], v173 offset:0x1800
	ds_read_b64_tr_b16 v[92:93], v173 offset:0x2000
	ds_read_b64_tr_b16 v[94:95], v173 offset:0x2800
	ds_read_b64_tr_b16 v[96:97], v173 offset:0x3000
	ds_read_b64_tr_b16 v[98:99], v173 offset:0x3800
	s_waitcnt lgkmcnt(0)
	v_fmac_f32_e32 v208, v196, v197
	v_permlane32_swap_b32_e32 v68, v70
	v_permlane32_swap_b32_e32 v69, v71
	v_permlane32_swap_b32_e32 v72, v74
	v_permlane32_swap_b32_e32 v73, v75
	v_permlane32_swap_b32_e32 v76, v78
	v_permlane32_swap_b32_e32 v77, v79
	v_permlane32_swap_b32_e32 v80, v82
	v_permlane32_swap_b32_e32 v81, v83
	v_mfma_f32_32x32x16_bf16 v[52:67], v[68:71], v[84:87], v[52:67]
	ds_read_b64_tr_b16 v[84:85], v173 offset:0x200
	ds_read_b64_tr_b16 v[86:87], v173 offset:0xa00
	v_mfma_f32_32x32x16_bf16 v[52:67], v[72:75], v[88:91], v[52:67]
	ds_read_b64_tr_b16 v[88:89], v173 offset:0x1200
	ds_read_b64_tr_b16 v[90:91], v173 offset:0x1a00
	v_mfma_f32_32x32x16_bf16 v[52:67], v[76:79], v[92:95], v[52:67]
	ds_read_b64_tr_b16 v[92:93], v173 offset:0x2200
	ds_read_b64_tr_b16 v[94:95], v173 offset:0x2a00
	v_mfma_f32_32x32x16_bf16 v[52:67], v[80:83], v[96:99], v[52:67]
	ds_read_b64_tr_b16 v[96:97], v173 offset:0x3200
	ds_read_b64_tr_b16 v[98:99], v173 offset:0x3a00
	s_waitcnt lgkmcnt(0)
	v_mfma_f32_32x32x16_bf16 v[36:51], v[68:71], v[84:87], v[36:51]
	ds_read_b64_tr_b16 v[84:85], v173 offset:0x400
	ds_read_b64_tr_b16 v[86:87], v173 offset:0xc00
	v_mfma_f32_32x32x16_bf16 v[36:51], v[72:75], v[88:91], v[36:51]
	ds_read_b64_tr_b16 v[88:89], v173 offset:0x1400
	ds_read_b64_tr_b16 v[90:91], v173 offset:0x1c00
	v_mfma_f32_32x32x16_bf16 v[36:51], v[76:79], v[92:95], v[36:51]
	ds_read_b64_tr_b16 v[92:93], v173 offset:0x2400
	ds_read_b64_tr_b16 v[94:95], v173 offset:0x2c00
	v_mfma_f32_32x32x16_bf16 v[36:51], v[80:83], v[96:99], v[36:51]
	ds_read_b64_tr_b16 v[96:97], v173 offset:0x3400
	ds_read_b64_tr_b16 v[98:99], v173 offset:0x3c00
	s_waitcnt lgkmcnt(0)
	v_mfma_f32_32x32x16_bf16 v[18:33], v[68:71], v[84:87], v[18:33]
	ds_read_b64_tr_b16 v[84:85], v173 offset:0x600
	ds_read_b64_tr_b16 v[86:87], v173 offset:0xe00
	v_mfma_f32_32x32x16_bf16 v[18:33], v[72:75], v[88:91], v[18:33]
	ds_read_b64_tr_b16 v[88:89], v173 offset:0x1600
	ds_read_b64_tr_b16 v[90:91], v173 offset:0x1e00
	v_mfma_f32_32x32x16_bf16 v[18:33], v[76:79], v[92:95], v[18:33]
	ds_read_b64_tr_b16 v[92:93], v173 offset:0x2600
	ds_read_b64_tr_b16 v[94:95], v173 offset:0x2e00
	v_mfma_f32_32x32x16_bf16 v[18:33], v[80:83], v[96:99], v[18:33]
	ds_read_b64_tr_b16 v[96:97], v173 offset:0x3600
	ds_read_b64_tr_b16 v[98:99], v173 offset:0x3e00
	s_waitcnt lgkmcnt(0)
	v_mfma_f32_32x32x16_bf16 v[2:17], v[68:71], v[84:87], v[2:17]
	v_mov_b32_e32 v196, v208
	v_mfma_f32_32x32x16_bf16 v[2:17], v[72:75], v[88:91], v[2:17]
	v_mfma_f32_32x32x16_bf16 v[2:17], v[76:79], v[92:95], v[2:17]
	v_mfma_f32_32x32x16_bf16 v[2:17], v[80:83], v[96:99], v[2:17]

.LBB0_511:
	v_exp_f32_e32 v84, v84
	v_exp_f32_e32 v85, v85
	v_exp_f32_e32 v86, v86
	v_exp_f32_e32 v87, v87
	v_add_f32_e32 v194, v194, v164
	v_exp_f32_e32 v88, v88
	v_add_f32_e32 v164, v85, v84
	v_exp_f32_e32 v89, v89
	v_add_f32_e32 v164, v86, v164
	v_exp_f32_e32 v90, v90
	v_add_f32_e32 v164, v87, v164
	v_exp_f32_e32 v91, v91
	v_add_f32_e32 v164, v88, v164
	v_exp_f32_e32 v92, v92
	v_add_f32_e32 v164, v89, v164
	v_exp_f32_e32 v93, v93
	v_add_f32_e32 v164, v90, v164
	v_exp_f32_e32 v94, v94
	v_add_f32_e32 v164, v91, v164
	v_exp_f32_e32 v95, v95
	v_add_f32_e32 v164, v92, v164
	v_exp_f32_e32 v96, v96
	v_add_f32_e32 v164, v93, v164
	v_exp_f32_e32 v97, v97
	v_add_f32_e32 v164, v94, v164
	v_exp_f32_e32 v98, v98
	v_add_f32_e32 v164, v95, v164
	v_exp_f32_e32 v99, v99
	v_add_f32_e32 v164, v96, v164
	v_exp_f32_e32 v180, v68
	v_add_f32_e32 v164, v97, v164
	v_exp_f32_e32 v181, v69
	v_add_f32_e32 v164, v98, v164
	v_exp_f32_e32 v182, v70
	v_add_f32_e32 v164, v99, v164
	v_exp_f32_e32 v183, v71
	v_add_f32_e32 v68, v180, v164
	v_exp_f32_e32 v164, v72
	v_add_f32_e32 v68, v181, v68
	v_exp_f32_e32 v198, v73
	v_add_f32_e32 v68, v182, v68
	v_exp_f32_e32 v199, v74
	v_add_f32_e32 v68, v183, v68
	v_exp_f32_e32 v200, v75
	v_add_f32_e32 v68, v164, v68
	v_exp_f32_e32 v201, v76
	v_add_f32_e32 v68, v198, v68
	v_exp_f32_e32 v202, v77
	v_add_f32_e32 v68, v199, v68
	v_exp_f32_e32 v203, v78
	v_add_f32_e32 v68, v200, v68
	v_exp_f32_e32 v204, v79
	v_add_f32_e32 v68, v201, v68
	v_exp_f32_e32 v205, v80
	v_add_f32_e32 v68, v202, v68
	v_exp_f32_e32 v206, v81
	v_add_f32_e32 v68, v203, v68
	v_exp_f32_e32 v207, v82
	v_add_f32_e32 v68, v204, v68
	v_exp_f32_e32 v83, v83
	v_add_f32_e32 v68, v205, v68
	v_add_f32_e32 v68, v206, v68
	v_add_f32_e32 v68, v207, v68
	v_add_f32_e32 v68, v83, v68
	v_mov_b32_e32 v69, v68
	s_nop 1
	v_permlane32_swap_b32_e32 v68, v69
	v_add_f32_e32 v208, v68, v69
	v_cvt_pk_bf16_f32 v68, v84, v85
	v_cvt_pk_bf16_f32 v69, v86, v87
	v_cvt_pk_bf16_f32 v70, v88, v89
	v_cvt_pk_bf16_f32 v71, v90, v91
	v_cvt_pk_bf16_f32 v72, v92, v93
	v_cvt_pk_bf16_f32 v73, v94, v95
	v_cvt_pk_bf16_f32 v74, v96, v97
	v_cvt_pk_bf16_f32 v75, v98, v99
	v_cvt_pk_bf16_f32 v76, v180, v181
	v_cvt_pk_bf16_f32 v77, v182, v183
	v_cvt_pk_bf16_f32 v78, v164, v198
	v_cvt_pk_bf16_f32 v79, v199, v200
	v_cvt_pk_bf16_f32 v80, v201, v202
	v_cvt_pk_bf16_f32 v81, v203, v204
	v_cvt_pk_bf16_f32 v82, v205, v206
	v_cvt_pk_bf16_f32 v83, v207, v83
	ds_read_b64_tr_b16 v[84:85], v191 offset:0
	ds_read_b64_tr_b16 v[86:87], v191 offset:0x800
	ds_read_b64_tr_b16 v[88:89], v191 offset:0x1000
	ds_read_b64_tr_b16 v[90:91], v191 offset:0x1800
	ds_read_b64_tr_b16 v[92:93], v191 offset:0x2000
	ds_read_b64_tr_b16 v[94:95], v191 offset:0x2800
	ds_read_b64_tr_b16 v[96:97], v191 offset:0x3000
	ds_read_b64_tr_b16 v[98:99], v191 offset:0x3800
	s_waitcnt lgkmcnt(0)
	v_fmac_f32_e32 v208, v196, v197
	v_permlane32_swap_b32_e32 v68, v70
	v_permlane32_swap_b32_e32 v69, v71
	v_permlane32_swap_b32_e32 v72, v74
	v_permlane32_swap_b32_e32 v73, v75
	v_permlane32_swap_b32_e32 v76, v78
	v_permlane32_swap_b32_e32 v77, v79
	v_permlane32_swap_b32_e32 v80, v82
	v_permlane32_swap_b32_e32 v81, v83
	v_mfma_f32_32x32x16_bf16 v[52:67], v[68:71], v[84:87], v[52:67]
	ds_read_b64_tr_b16 v[84:85], v191 offset:0x200
	ds_read_b64_tr_b16 v[86:87], v191 offset:0xa00
	v_mfma_f32_32x32x16_bf16 v[52:67], v[72:75], v[88:91], v[52:67]
	ds_read_b64_tr_b16 v[88:89], v191 offset:0x1200
	ds_read_b64_tr_b16 v[90:91], v191 offset:0x1a00
	v_mfma_f32_32x32x16_bf16 v[52:67], v[76:79], v[92:95], v[52:67]
	ds_read_b64_tr_b16 v[92:93], v191 offset:0x2200
	ds_read_b64_tr_b16 v[94:95], v191 offset:0x2a00
	v_mfma_f32_32x32x16_bf16 v[52:67], v[80:83], v[96:99], v[52:67]
	ds_read_b64_tr_b16 v[96:97], v191 offset:0x3200
	ds_read_b64_tr_b16 v[98:99], v191 offset:0x3a00
	s_waitcnt lgkmcnt(0)
	v_mfma_f32_32x32x16_bf16 v[36:51], v[68:71], v[84:87], v[36:51]
	ds_read_b64_tr_b16 v[84:85], v191 offset:0x400
	ds_read_b64_tr_b16 v[86:87], v191 offset:0xc00
	v_mfma_f32_32x32x16_bf16 v[36:51], v[72:75], v[88:91], v[36:51]
	ds_read_b64_tr_b16 v[88:89], v191 offset:0x1400
	ds_read_b64_tr_b16 v[90:91], v191 offset:0x1c00
	v_mfma_f32_32x32x16_bf16 v[36:51], v[76:79], v[92:95], v[36:51]
	ds_read_b64_tr_b16 v[92:93], v191 offset:0x2400
	ds_read_b64_tr_b16 v[94:95], v191 offset:0x2c00
	v_mfma_f32_32x32x16_bf16 v[36:51], v[80:83], v[96:99], v[36:51]
	ds_read_b64_tr_b16 v[96:97], v191 offset:0x3400
	ds_read_b64_tr_b16 v[98:99], v191 offset:0x3c00
	s_waitcnt lgkmcnt(0)
	v_mfma_f32_32x32x16_bf16 v[18:33], v[68:71], v[84:87], v[18:33]
	ds_read_b64_tr_b16 v[84:85], v191 offset:0x600
	ds_read_b64_tr_b16 v[86:87], v191 offset:0xe00
	v_mfma_f32_32x32x16_bf16 v[18:33], v[72:75], v[88:91], v[18:33]
	ds_read_b64_tr_b16 v[88:89], v191 offset:0x1600
	ds_read_b64_tr_b16 v[90:91], v191 offset:0x1e00
	v_mfma_f32_32x32x16_bf16 v[18:33], v[76:79], v[92:95], v[18:33]
	ds_read_b64_tr_b16 v[92:93], v191 offset:0x2600
	ds_read_b64_tr_b16 v[94:95], v191 offset:0x2e00
	v_mfma_f32_32x32x16_bf16 v[18:33], v[80:83], v[96:99], v[18:33]
	ds_read_b64_tr_b16 v[96:97], v191 offset:0x3600
	ds_read_b64_tr_b16 v[98:99], v191 offset:0x3e00
	s_waitcnt lgkmcnt(0)
	v_mfma_f32_32x32x16_bf16 v[2:17], v[68:71], v[84:87], v[2:17]
	v_mov_b32_e32 v196, v208
	v_mfma_f32_32x32x16_bf16 v[2:17], v[72:75], v[88:91], v[2:17]
	v_mfma_f32_32x32x16_bf16 v[2:17], v[76:79], v[92:95], v[2:17]
	v_mfma_f32_32x32x16_bf16 v[2:17], v[80:83], v[96:99], v[2:17]
	s_andn2_b64 vcc, exec, s[28:29]
	s_cbranch_vccnz .LBB0_515
